# v38 + dense unit prologue (mref once per phase, K2 DMA before Q wait) + SW attention K/V register double buffering (loads 2 tiles ahead)
# baseline (speedup 1.0000x reference)
; #define LAS __attribute__((address_space(3)))
; #define SA_LOAD(tbase) do { const bf16* kp_ = Kp + (size_t)((tbase) + r32) * kvpitch + 8 * hi; \
;         _Pragma("unroll") for (int ks = 0; ks < 4; ++ks) kf[ks] = *(const bf16x8*)(kp_ + 16 * ks); \
;         _Pragma("unroll") for (int e = 0; e < 4; ++e) { const int c = lane + 64 * e; vr[e] = *(const v4u*)(Vp + (size_t)((tbase) + (c >> 3)) * kvpitch + (c & 7) * 8); } } while (0)
; #define SA_VWRITE(buf) do { _Pragma("unroll") for (int e = 0; e < 4; ++e) { const int c = lane + 64 * e; *(LAS v4u*)(wl + (buf) * 4608 + (c >> 3) * 144 + (c & 7) * 16) = vr[e]; } } while (0)
; #define SA_QK(X) do { _Pragma("unroll") for (int ks = 0; ks < 4; ++ks) X = __builtin_amdgcn_mfma_f32_32x32x16_bf16(kf[ks], qf[ks], X, 0, 0, 0); } while (0)
; template <int MODE> ...
;     ...
;       auto rr = __builtin_amdgcn_permlane32_swap(__float_as_uint(qs), __float_as_uint(qs), false, false); qs = __uint_as_float(rr[0]) + __uint_as_float(rr[1]);
;       const float k2 = __uint_as_float(kmax2[0]) + __uint_as_float(kmax2[1]);
;       ref = fminf(__builtin_sqrtf(qs * k2) * 1.03f + bmx, 110.0f); }
;     f32x16 o0 = {}, o1 = {};
;     float lsum = 0.f;
;     const int i16 = lane & 15, g16 = (lane >> 4) & 1;
;     LAS unsigned char* vaddr = wl + (4 * hi + (i16 >> 2)) * 144 + g16 * 32 + 8 * (i16 & 3);
;     f32x16 xa_, xb_;
;     SA_VWRITE(0); SA_CINIT(0, xa_); SA_QK(xa_);
;     if (nt > 1) SA_LOAD(tb0 + tstep);
;     ...
;     for (int i = 0; i < nt; i += 2) {
.LBB0_502:
	s_waitcnt lgkmcnt(0)
	v_mfma_f32_32x32x16_bf16 v[0:15], v[80:83], v[64:67], v[0:15]
	s_min_i32 s0, s31, 0x3f60
	s_sub_i32 s0, s0, s30
	s_addk_i32 s0, 0x120
	s_ashr_i32 s31, s0, 5
	s_cmp_lt_i32 s31, 2
	v_mfma_f32_32x32x16_bf16 v[0:15], v[84:87], v[68:71], v[0:15]
	v_mfma_f32_32x32x16_bf16 v[0:15], v[88:91], v[72:75], v[0:15]
	v_mfma_f32_32x32x16_bf16 v[0:15], v[92:95], v[76:79], v[0:15]
	s_waitcnt vmcnt(0)
	s_cbranch_scc1 .LBB0_504
	s_add_i32 s0, s30, 0xffffffa0
	v_or_b32_e32 v22, s0, v113
	v_mov_b32_e32 v23, v129
	v_lshlrev_b64 v[22:23], 8, v[22:23]
	v_lshl_add_u64 v[22:23], s[44:45], 0, v[22:23]
	v_lshl_add_u64 v[22:23], v[22:23], 0, v[128:129]
	global_load_dwordx4 v[80:83], v[22:23], off
	global_load_dwordx4 v[84:87], v[22:23], off offset:32
	global_load_dwordx4 v[88:91], v[22:23], off offset:64
	global_load_dwordx4 v[92:95], v[22:23], off offset:96
	v_or_b32_e32 v22, s0, v150
	v_mov_b32_e32 v23, v129
	v_lshlrev_b64 v[22:23], 8, v[22:23]
	v_or_b32_e32 v24, s0, v151
	v_mov_b32_e32 v25, v129
	v_lshl_add_u64 v[22:23], v[126:127], 0, v[22:23]
	v_lshlrev_b64 v[24:25], 8, v[24:25]
	v_lshl_add_u64 v[24:25], v[126:127], 0, v[24:25]
	global_load_dwordx4 v[96:99], v[22:23], off
	global_load_dwordx4 v[100:103], v[24:25], off
	v_or_b32_e32 v22, s0, v152
	v_mov_b32_e32 v23, v129
	v_lshlrev_b64 v[22:23], 8, v[22:23]
	v_or_b32_e32 v24, s0, v153
	v_mov_b32_e32 v25, v129
	v_lshl_add_u64 v[22:23], v[126:127], 0, v[22:23]
	v_lshlrev_b64 v[24:25], 8, v[24:25]
	v_lshl_add_u64 v[24:25], v[126:127], 0, v[24:25]
	global_load_dwordx4 v[104:107], v[22:23], off
	global_load_dwordx4 v[108:111], v[24:25], off
	s_lshl_b32 s100, s31, 5
	s_add_i32 s100, s100, s30
	s_addk_i32 s100, 0xff60
	s_add_i32 s0, s30, 0xffffffc0
	s_min_i32 s0, s0, s100
	v_or_b32_e32 v22, s0, v113
	v_mov_b32_e32 v23, v129
	v_lshlrev_b64 v[22:23], 8, v[22:23]
	v_lshl_add_u64 v[22:23], s[44:45], 0, v[22:23]
	v_lshl_add_u64 v[22:23], v[22:23], 0, v[128:129]
	global_load_dwordx4 v[208:211], v[22:23], off
	global_load_dwordx4 v[212:215], v[22:23], off offset:32
	global_load_dwordx4 v[216:219], v[22:23], off offset:64
	global_load_dwordx4 v[220:223], v[22:23], off offset:96
	v_or_b32_e32 v22, s0, v150
	v_mov_b32_e32 v23, v129
	v_lshlrev_b64 v[22:23], 8, v[22:23]
	v_or_b32_e32 v24, s0, v151
	v_mov_b32_e32 v25, v129
	v_lshl_add_u64 v[22:23], v[126:127], 0, v[22:23]
	v_lshlrev_b64 v[24:25], 8, v[24:25]
	v_lshl_add_u64 v[24:25], v[126:127], 0, v[24:25]
	global_load_dwordx4 v[238:241], v[22:23], off
	global_load_dwordx4 v[242:245], v[24:25], off
	v_or_b32_e32 v22, s0, v152
	v_mov_b32_e32 v23, v129
	v_lshlrev_b64 v[22:23], 8, v[22:23]
	v_or_b32_e32 v24, s0, v153
	v_mov_b32_e32 v25, v129
	v_lshl_add_u64 v[22:23], v[126:127], 0, v[22:23]
	v_lshlrev_b64 v[24:25], 8, v[24:25]
	v_lshl_add_u64 v[24:25], v[126:127], 0, v[24:25]
	global_load_dwordx4 v[246:249], v[22:23], off
	global_load_dwordx4 v[202:205], v[24:25], off
.LBB0_504:
	v_add_f32_e32 v20, v20, v21
	v_add_f32_e32 v16, v16, v17
	v_mul_f32_e32 v16, v20, v16
	v_mul_f32_e32 v17, 0x4f800000, v16
	v_cmp_gt_f32_e32 vcc, s88, v16
	v_max_f32_e32 v19, v19, v19
	v_max_f32_e32 v18, v18, v18
	v_cndmask_b32_e32 v16, v16, v17, vcc
	v_sqrt_f32_e32 v17, v16
	v_max_f32_e32 v18, v18, v19
	v_mov_b32_e32 v31, 0
	s_cmp_lt_i32 s31, 1
	v_add_u32_e32 v19, -1, v17
	v_fma_f32 v20, -v19, v17, v16
	v_cmp_ge_f32_e64 s[0:1], 0, v20
	v_add_u32_e32 v20, 1, v17
	v_mov_b32_e32 v30, v31
	v_cndmask_b32_e64 v19, v17, v19, s[0:1]
	v_fma_f32 v17, -v20, v17, v16
	v_cmp_lt_f32_e64 s[0:1], 0, v17
	v_mov_b32_e32 v29, v31
	v_mov_b32_e32 v28, v31
	v_cndmask_b32_e64 v17, v19, v20, s[0:1]
	v_mul_f32_e32 v19, 0x37800000, v17
	v_cndmask_b32_e32 v17, v17, v19, vcc
	v_cmp_class_f32_e32 vcc, v16, v229
	v_mov_b32_e32 v27, v31
	v_mov_b32_e32 v26, v31
	v_cndmask_b32_e32 v16, v17, v16, vcc
	v_fmac_f32_e32 v18, 0x3f83d70a, v16
	v_min_f32_e32 v123, 0x42dc0000, v18
	v_mov_b32_e32 v25, v31
	v_mov_b32_e32 v24, v31
	v_mov_b32_e32 v23, v31
	v_mov_b32_e32 v22, v31
	v_mov_b32_e32 v21, v31
	v_mov_b32_e32 v20, v31
	v_mov_b32_e32 v19, v31
	v_mov_b32_e32 v18, v31
	v_mov_b32_e32 v17, v31
	v_mov_b32_e32 v16, v31
	v_mov_b32_e32 v47, v31
	v_mov_b32_e32 v46, v31
	v_mov_b32_e32 v45, v31
	v_mov_b32_e32 v44, v31
	v_mov_b32_e32 v43, v31
	v_mov_b32_e32 v42, v31
	v_mov_b32_e32 v41, v31
	v_mov_b32_e32 v40, v31
	v_mov_b32_e32 v39, v31
	v_mov_b32_e32 v38, v31
	v_mov_b32_e32 v37, v31
	v_mov_b32_e32 v36, v31
	v_mov_b32_e32 v35, v31
	v_mov_b32_e32 v34, v31
	v_mov_b32_e32 v33, v31
	v_mov_b32_e32 v32, v31
	v_mov_b32_e32 v169, v31
	s_cbranch_scc1 .LBB0_590
	s_and_b32 s1, s4, 63
	s_lshl_b32 s0, s30, 2
	s_lshl_b32 s1, s1, 10
	s_sub_i32 s0, s0, s1
	v_mov_b32_e32 v169, 0
	s_add_i32 s34, s31, -2
	v_lshl_add_u64 v[130:131], s[44:45], 0, v[128:129]
	s_add_i32 s37, s31, -3
	v_add_u32_e32 v128, s0, v119
	s_sub_i32 s44, s21, s5
	v_sub_u32_e32 v170, v116, v124
	s_mov_b32 s45, 0
	v_mov_b32_e32 v16, 0
	v_mov_b32_e32 v17, v169
	v_mov_b32_e32 v18, v169
	v_mov_b32_e32 v19, v169
	v_mov_b32_e32 v20, v169
	v_mov_b32_e32 v21, v169
	v_mov_b32_e32 v22, v169
	v_mov_b32_e32 v23, v169
	v_mov_b32_e32 v24, v169
	v_mov_b32_e32 v25, v169
	v_mov_b32_e32 v26, v169
	v_mov_b32_e32 v27, v169
	v_mov_b32_e32 v28, v169
	v_mov_b32_e32 v29, v169
	v_mov_b32_e32 v30, v169
	v_mov_b32_e32 v31, v169
	v_mov_b32_e32 v32, 0
	v_mov_b32_e32 v33, v169
	v_mov_b32_e32 v34, v169
	v_mov_b32_e32 v35, v169
	v_mov_b32_e32 v36, v169
	v_mov_b32_e32 v37, v169
	v_mov_b32_e32 v38, v169
	v_mov_b32_e32 v39, v169
	v_mov_b32_e32 v40, v169
	v_mov_b32_e32 v41, v169
	v_mov_b32_e32 v42, v169
	v_mov_b32_e32 v43, v169
	v_mov_b32_e32 v44, v169
	v_mov_b32_e32 v45, v169
	v_mov_b32_e32 v46, v169
	v_mov_b32_e32 v47, v169
.LBB0_506:
	s_add_i32 s0, s45, 1
	s_cmp_ge_i32 s0, s31
	s_cselect_b64 s[0:1], -1, 0
	s_and_b64 vcc, exec, s[0:1]
	s_cbranch_vccnz .LBB0_545
	s_add_i32 s4, s44, s30
	s_cmpk_lt_u32 s4, 0xc1
	s_mov_b64 s[4:5], -1
	s_waitcnt vmcnt(11)
	ds_write_b128 v166, v[96:99] offset:4608
	s_waitcnt vmcnt(10)
	ds_write_b128 v166, v[100:103] offset:5760
	s_waitcnt vmcnt(9)
	ds_write_b128 v166, v[104:107] offset:6912
	s_waitcnt vmcnt(8)
	ds_write_b128 v166, v[108:111] offset:8064
	s_cbranch_scc1 .LBB0_541
	v_add_u32_e32 v171, s30, v170
	v_add_u32_e32 v48, 32, v171
	v_cmp_gt_u32_e32 vcc, s33, v48
	v_mov_b32_e32 v49, 0xf149f2ca
	v_mov_b32_e32 v48, 0xf149f2ca
	s_and_saveexec_b64 s[4:5], vcc
	ds_read_b32 v48, v128
	s_or_b64 exec, exec, s[4:5]
	v_add_u32_e32 v50, 33, v171
	v_cmp_gt_u32_e32 vcc, s33, v50
	s_and_saveexec_b64 s[4:5], vcc
	ds_read_b32 v49, v128 offset:4
	s_or_b64 exec, exec, s[4:5]
	v_add_u32_e32 v50, 34, v171
	v_cmp_gt_u32_e32 vcc, s33, v50
	v_mov_b32_e32 v51, 0xf149f2ca
	v_mov_b32_e32 v50, 0xf149f2ca
	s_and_saveexec_b64 s[4:5], vcc
	ds_read_b32 v50, v128 offset:8
	s_or_b64 exec, exec, s[4:5]
	v_add_u32_e32 v52, 35, v171
	v_cmp_gt_u32_e32 vcc, s33, v52
	s_and_saveexec_b64 s[4:5], vcc
	ds_read_b32 v51, v128 offset:12
	s_or_b64 exec, exec, s[4:5]
	v_add_u32_e32 v52, 40, v171
	v_cmp_gt_u32_e32 vcc, s33, v52
	v_mov_b32_e32 v53, 0xf149f2ca
	v_mov_b32_e32 v52, 0xf149f2ca
	s_and_saveexec_b64 s[4:5], vcc
	ds_read_b32 v52, v128 offset:32
	s_or_b64 exec, exec, s[4:5]
	v_add_u32_e32 v54, 41, v171
	v_cmp_gt_u32_e32 vcc, s33, v54
	s_and_saveexec_b64 s[4:5], vcc
	ds_read_b32 v53, v128 offset:36
	s_or_b64 exec, exec, s[4:5]
	v_add_u32_e32 v54, 42, v171
	v_cmp_gt_u32_e32 vcc, s33, v54
	v_mov_b32_e32 v55, 0xf149f2ca
	v_mov_b32_e32 v54, 0xf149f2ca
	s_and_saveexec_b64 s[4:5], vcc
	ds_read_b32 v54, v128 offset:40
	s_or_b64 exec, exec, s[4:5]
	v_add_u32_e32 v56, 43, v171
	v_cmp_gt_u32_e32 vcc, s33, v56
	s_and_saveexec_b64 s[4:5], vcc
	ds_read_b32 v55, v128 offset:44
	s_or_b64 exec, exec, s[4:5]
	v_add_u32_e32 v56, 48, v171
	v_cmp_gt_u32_e32 vcc, s33, v56
	v_mov_b32_e32 v57, 0xf149f2ca
	v_mov_b32_e32 v56, 0xf149f2ca
	s_and_saveexec_b64 s[4:5], vcc
	ds_read_b32 v56, v128 offset:64
	s_or_b64 exec, exec, s[4:5]
	v_add_u32_e32 v58, 49, v171
	v_cmp_gt_u32_e32 vcc, s33, v58
	s_and_saveexec_b64 s[4:5], vcc
	ds_read_b32 v57, v128 offset:68
	s_or_b64 exec, exec, s[4:5]
	v_add_u32_e32 v58, 50, v171
	v_cmp_gt_u32_e32 vcc, s33, v58
	v_mov_b32_e32 v59, 0xf149f2ca
	v_mov_b32_e32 v58, 0xf149f2ca
	s_and_saveexec_b64 s[4:5], vcc
	ds_read_b32 v58, v128 offset:72
	s_or_b64 exec, exec, s[4:5]
	v_add_u32_e32 v60, 51, v171
	v_cmp_gt_u32_e32 vcc, s33, v60
	s_and_saveexec_b64 s[4:5], vcc
	ds_read_b32 v59, v128 offset:76
	s_or_b64 exec, exec, s[4:5]
	v_add_u32_e32 v60, 56, v171
	v_cmp_gt_u32_e32 vcc, s33, v60
	v_mov_b32_e32 v61, 0xf149f2ca
	v_mov_b32_e32 v60, 0xf149f2ca
	s_and_saveexec_b64 s[4:5], vcc
	ds_read_b32 v60, v128 offset:96
	s_or_b64 exec, exec, s[4:5]
	v_add_u32_e32 v62, 57, v171
	v_cmp_gt_u32_e32 vcc, s33, v62
	s_and_saveexec_b64 s[4:5], vcc
	ds_read_b32 v61, v128 offset:100
	s_or_b64 exec, exec, s[4:5]
	v_add_u32_e32 v62, 58, v171
	v_cmp_gt_u32_e32 vcc, s33, v62
	v_mov_b32_e32 v63, 0xf149f2ca
	v_mov_b32_e32 v62, 0xf149f2ca
	s_and_saveexec_b64 s[4:5], vcc
	ds_read_b32 v62, v128 offset:104
	s_or_b64 exec, exec, s[4:5]
	v_add_u32_e32 v171, 59, v171
	v_cmp_gt_u32_e32 vcc, s33, v171
	s_and_saveexec_b64 s[4:5], vcc
	ds_read_b32 v63, v128 offset:108
	s_or_b64 exec, exec, s[4:5]
	s_mov_b64 s[4:5], 0

.LBB0_543:
	s_waitcnt lgkmcnt(0)
	v_mfma_f32_32x32x16_bf16 v[48:63], v[80:83], v[64:67], v[48:63]
	s_cmp_ge_i32 s45, s34
	v_mfma_f32_32x32x16_bf16 v[48:63], v[84:87], v[68:71], v[48:63]
	v_mfma_f32_32x32x16_bf16 v[48:63], v[88:91], v[72:75], v[48:63]
	v_mfma_f32_32x32x16_bf16 v[48:63], v[92:95], v[76:79], v[48:63]
	s_add_i32 s99, s30, -32
	s_min_i32 s99, s99, s100
	s_add_i32 s99, s99, 64
	v_add_u32_e32 v80, s99, v113
	v_subrev_u32_e32 v80, 64, v80
	v_ashrrev_i32_e32 v81, 31, v80
	v_add_u32_e32 v106, s99, v150
	v_lshlrev_b64 v[80:81], 8, v[80:81]
	v_subrev_u32_e32 v96, 64, v106
	v_subrev_u32_e32 v98, 56, v106
	v_subrev_u32_e32 v104, 48, v106
	v_subrev_u32_e32 v106, 40, v106
	v_lshl_add_u64 v[92:93], v[130:131], 0, v[80:81]
	v_ashrrev_i32_e32 v97, 31, v96
	v_ashrrev_i32_e32 v99, 31, v98
	v_ashrrev_i32_e32 v105, 31, v104
	v_ashrrev_i32_e32 v107, 31, v106
	global_load_dwordx4 v[80:83], v[92:93], off
	global_load_dwordx4 v[84:87], v[92:93], off offset:32
	global_load_dwordx4 v[88:91], v[92:93], off offset:64
	s_nop 0
	global_load_dwordx4 v[92:95], v[92:93], off offset:96
	v_lshlrev_b64 v[96:97], 8, v[96:97]
	v_lshlrev_b64 v[98:99], 8, v[98:99]
	v_lshlrev_b64 v[104:105], 8, v[104:105]
	v_lshlrev_b64 v[106:107], 8, v[106:107]
	v_lshl_add_u64 v[96:97], v[126:127], 0, v[96:97]
	v_lshl_add_u64 v[100:101], v[126:127], 0, v[98:99]
	v_lshl_add_u64 v[104:105], v[126:127], 0, v[104:105]
	v_lshl_add_u64 v[108:109], v[126:127], 0, v[106:107]
	global_load_dwordx4 v[96:99], v[96:97], off
	s_nop 0
	global_load_dwordx4 v[100:103], v[100:101], off
	s_nop 0
	global_load_dwordx4 v[104:107], v[104:105], off
	s_nop 0
	global_load_dwordx4 v[108:111], v[108:109], off

.LBB0_547:
	v_add_f32_e32 v171, 0, v0
	v_add_f32_e32 v171, v1, v171
	v_add_f32_e32 v171, v2, v171
	v_add_f32_e32 v171, v3, v171
	v_add_f32_e32 v171, v4, v171
	v_add_f32_e32 v171, v5, v171
	v_add_f32_e32 v171, v6, v171
	v_add_f32_e32 v171, v7, v171
	v_add_f32_e32 v171, v8, v171
	v_add_f32_e32 v171, v9, v171
	v_add_f32_e32 v171, v10, v171
	v_add_f32_e32 v171, v11, v171
	v_add_f32_e32 v171, v12, v171
	v_add_f32_e32 v171, v13, v171
	v_add_f32_e32 v171, v14, v171
	v_add_f32_e32 v171, v15, v171
	s_andn2_b64 vcc, exec, s[0:1]
	v_add_f32_e32 v169, v169, v171
	s_cbranch_vccnz .LBB0_588
	s_add_i32 s4, s45, 2
	s_cmp_ge_i32 s4, s31
	s_cbranch_scc1 .LBB0_587
	s_add_i32 s0, s44, s30
	s_add_i32 s0, s0, 32
	s_cmpk_lt_u32 s0, 0xc1
	s_mov_b64 s[0:1], -1
	s_waitcnt vmcnt(11)
	ds_write_b128 v166, v[238:241]
	s_waitcnt vmcnt(10)
	ds_write_b128 v166, v[242:245] offset:1152
	s_waitcnt vmcnt(9)
	ds_write_b128 v166, v[246:249] offset:2304
	s_waitcnt vmcnt(8)
	ds_write_b128 v166, v[202:205] offset:3456
	s_cbranch_scc1 .LBB0_583
	v_add_u32_e32 v171, s30, v170
	v_add_u32_e32 v0, 64, v171
	v_cmp_gt_u32_e32 vcc, s33, v0
	v_mov_b32_e32 v1, 0xf149f2ca
	v_mov_b32_e32 v0, 0xf149f2ca
	s_and_saveexec_b64 s[0:1], vcc
	ds_read_b32 v0, v128 offset:128
	s_or_b64 exec, exec, s[0:1]
	v_add_u32_e32 v2, 0x41, v171
	v_cmp_gt_u32_e32 vcc, s33, v2
	s_and_saveexec_b64 s[0:1], vcc
	ds_read_b32 v1, v128 offset:132
	s_or_b64 exec, exec, s[0:1]
	v_add_u32_e32 v2, 0x42, v171
	v_cmp_gt_u32_e32 vcc, s33, v2
	v_mov_b32_e32 v3, 0xf149f2ca
	v_mov_b32_e32 v2, 0xf149f2ca
	s_and_saveexec_b64 s[0:1], vcc
	ds_read_b32 v2, v128 offset:136
	s_or_b64 exec, exec, s[0:1]
	v_add_u32_e32 v4, 0x43, v171
	v_cmp_gt_u32_e32 vcc, s33, v4
	s_and_saveexec_b64 s[0:1], vcc
	ds_read_b32 v3, v128 offset:140
	s_or_b64 exec, exec, s[0:1]
	v_add_u32_e32 v4, 0x48, v171
	v_cmp_gt_u32_e32 vcc, s33, v4
	v_mov_b32_e32 v5, 0xf149f2ca
	v_mov_b32_e32 v4, 0xf149f2ca
	s_and_saveexec_b64 s[0:1], vcc
	ds_read_b32 v4, v128 offset:160
	s_or_b64 exec, exec, s[0:1]
	v_add_u32_e32 v6, 0x49, v171
	v_cmp_gt_u32_e32 vcc, s33, v6
	s_and_saveexec_b64 s[0:1], vcc
	ds_read_b32 v5, v128 offset:164
	s_or_b64 exec, exec, s[0:1]
	v_add_u32_e32 v6, 0x4a, v171
	v_cmp_gt_u32_e32 vcc, s33, v6
	v_mov_b32_e32 v7, 0xf149f2ca
	v_mov_b32_e32 v6, 0xf149f2ca
	s_and_saveexec_b64 s[0:1], vcc
	ds_read_b32 v6, v128 offset:168
	s_or_b64 exec, exec, s[0:1]
	v_add_u32_e32 v8, 0x4b, v171
	v_cmp_gt_u32_e32 vcc, s33, v8
	s_and_saveexec_b64 s[0:1], vcc
	ds_read_b32 v7, v128 offset:172
	s_or_b64 exec, exec, s[0:1]
	v_add_u32_e32 v8, 0x50, v171
	v_cmp_gt_u32_e32 vcc, s33, v8
	v_mov_b32_e32 v9, 0xf149f2ca
	v_mov_b32_e32 v8, 0xf149f2ca
	s_and_saveexec_b64 s[0:1], vcc
	ds_read_b32 v8, v128 offset:192
	s_or_b64 exec, exec, s[0:1]
	v_add_u32_e32 v10, 0x51, v171
	v_cmp_gt_u32_e32 vcc, s33, v10
	s_and_saveexec_b64 s[0:1], vcc
	ds_read_b32 v9, v128 offset:196
	s_or_b64 exec, exec, s[0:1]
	v_add_u32_e32 v10, 0x52, v171
	v_cmp_gt_u32_e32 vcc, s33, v10
	v_mov_b32_e32 v11, 0xf149f2ca
	v_mov_b32_e32 v10, 0xf149f2ca
	s_and_saveexec_b64 s[0:1], vcc
	ds_read_b32 v10, v128 offset:200
	s_or_b64 exec, exec, s[0:1]
	v_add_u32_e32 v12, 0x53, v171
	v_cmp_gt_u32_e32 vcc, s33, v12
	s_and_saveexec_b64 s[0:1], vcc
	ds_read_b32 v11, v128 offset:204
	s_or_b64 exec, exec, s[0:1]
	v_add_u32_e32 v12, 0x58, v171
	v_cmp_gt_u32_e32 vcc, s33, v12
	v_mov_b32_e32 v13, 0xf149f2ca
	v_mov_b32_e32 v12, 0xf149f2ca
	s_and_saveexec_b64 s[0:1], vcc
	ds_read_b32 v12, v128 offset:224
	s_or_b64 exec, exec, s[0:1]
	v_add_u32_e32 v14, 0x59, v171
	v_cmp_gt_u32_e32 vcc, s33, v14
	s_and_saveexec_b64 s[0:1], vcc
	ds_read_b32 v13, v128 offset:228
	s_or_b64 exec, exec, s[0:1]
	v_add_u32_e32 v14, 0x5a, v171
	v_cmp_gt_u32_e32 vcc, s33, v14
	v_mov_b32_e32 v15, 0xf149f2ca
	v_mov_b32_e32 v14, 0xf149f2ca
	s_and_saveexec_b64 s[0:1], vcc
	ds_read_b32 v14, v128 offset:232
	s_or_b64 exec, exec, s[0:1]
	v_add_u32_e32 v171, 0x5b, v171
	v_cmp_gt_u32_e32 vcc, s33, v171
	s_and_saveexec_b64 s[0:1], vcc
	ds_read_b32 v15, v128 offset:236
	s_or_b64 exec, exec, s[0:1]
	s_mov_b64 s[0:1], 0

.LBB0_585:
	s_waitcnt lgkmcnt(0)
	v_mfma_f32_32x32x16_bf16 v[0:15], v[208:211], v[64:67], v[0:15]
	s_cmp_ge_i32 s45, s37
	v_mfma_f32_32x32x16_bf16 v[0:15], v[212:215], v[68:71], v[0:15]
	v_mfma_f32_32x32x16_bf16 v[0:15], v[216:219], v[72:75], v[0:15]
	v_mfma_f32_32x32x16_bf16 v[0:15], v[220:223], v[76:79], v[0:15]
	s_min_i32 s99, s30, s100
	s_add_i32 s99, s99, 32
	v_add_u32_e32 v208, s99, v113
	v_subrev_u32_e32 v208, 32, v208
	v_ashrrev_i32_e32 v209, 31, v208
	v_add_u32_e32 v248, s99, v150
	v_lshlrev_b64 v[208:209], 8, v[208:209]
	v_subrev_u32_e32 v238, 32, v248
	v_subrev_u32_e32 v240, 24, v248
	v_add_u32_e32 v246, -16, v248
	v_add_u32_e32 v248, -8, v248
	v_lshl_add_u64 v[220:221], v[130:131], 0, v[208:209]
	v_ashrrev_i32_e32 v239, 31, v238
	v_ashrrev_i32_e32 v241, 31, v240
	v_ashrrev_i32_e32 v247, 31, v246
	v_ashrrev_i32_e32 v249, 31, v248
	global_load_dwordx4 v[208:211], v[220:221], off
	global_load_dwordx4 v[212:215], v[220:221], off offset:32
	global_load_dwordx4 v[216:219], v[220:221], off offset:64
	s_nop 0
	global_load_dwordx4 v[220:223], v[220:221], off offset:96
	v_lshlrev_b64 v[238:239], 8, v[238:239]
	v_lshlrev_b64 v[240:241], 8, v[240:241]
	v_lshlrev_b64 v[246:247], 8, v[246:247]
	v_lshlrev_b64 v[248:249], 8, v[248:249]
	v_lshl_add_u64 v[238:239], v[126:127], 0, v[238:239]
	v_lshl_add_u64 v[242:243], v[126:127], 0, v[240:241]
	v_lshl_add_u64 v[246:247], v[126:127], 0, v[246:247]
	v_lshl_add_u64 v[202:203], v[126:127], 0, v[248:249]
	global_load_dwordx4 v[238:241], v[238:239], off
	s_nop 0
	global_load_dwordx4 v[242:245], v[242:243], off
	s_nop 0
	global_load_dwordx4 v[246:249], v[246:247], off
	s_nop 0
	global_load_dwordx4 v[202:205], v[202:203], off

; template <int MODE> ...
;     ...
;     { auto rr = __builtin_amdgcn_permlane32_swap(__float_as_uint(lsum), __float_as_uint(lsum), false, false); lsum = __uint_as_float(rr[0]) + __uint_as_float(rr[1]); }
;     if (MODE == 0) lsum += __builtin_amdgcn_exp2f(sink2 - ref);
;     const float inv = 1.0f / lsum;
;     { float ss = 0.f;
; #pragma unroll
;       for (int e = 0; e < 16; ++e) { const float a0 = o0[e] * inv, a1 = o1[e] * inv; ss += a0 * a0 + a1 * a1; }
;       auto rr = __builtin_amdgcn_permlane32_swap(__float_as_uint(ss), __float_as_uint(ss), false, false); ss = __uint_as_float(rr[0]) + __uint_as_float(rr[1]);
;       if (hi == 0) atomicAdd(gssrow + qtok, ss); }
.LBB0_590:
	s_waitcnt vmcnt(0)
	s_mov_b32 s0, 0x3fb8aa3b
	v_fma_f32 v1, v168, s0, -v123
	v_exp_f32_e32 v1, v1
	v_mov_b32_e32 v0, v169
	s_nop 1
	v_permlane32_swap_b32_e32 v169, v0
	v_add_f32_e32 v0, v169, v0
	v_add_f32_e32 v0, v1, v0
	v_div_scale_f32 v1, s[0:1], v0, v0, 1.0
	v_rcp_f32_e32 v2, v1
	s_nop 0
	v_fma_f32 v3, -v1, v2, 1.0
	v_fmac_f32_e32 v2, v3, v2
	v_div_scale_f32 v3, vcc, 1.0, v0, 1.0
	v_mul_f32_e32 v4, v3, v2
	v_fma_f32 v5, -v1, v4, v3
	v_fmac_f32_e32 v4, v5, v2
	v_fma_f32 v1, -v1, v4, v3
	v_div_fmas_f32 v1, v1, v2, v4
	v_div_fixup_f32 v48, v1, v0, 1.0
	v_pk_mul_f32 v[0:1], v[32:33], v[48:49] op_sel_hi:[1,0]
	v_pk_mul_f32 v[2:3], v[16:17], v[48:49] op_sel_hi:[1,0]
	v_pk_mul_f32 v[4:5], v[0:1], v[0:1]
	v_pk_mul_f32 v[8:9], v[18:19], v[48:49] op_sel_hi:[1,0]
	v_pk_fma_f32 v[4:5], v[2:3], v[2:3], v[4:5]
	v_pk_mul_f32 v[16:17], v[22:23], v[48:49] op_sel_hi:[1,0]
	v_pk_add_f32 v[6:7], v[4:5], v[4:5] op_sel:[0,1] op_sel_hi:[1,0]
	v_pk_mul_f32 v[4:5], v[34:35], v[48:49] op_sel_hi:[1,0]
	v_pk_mul_f32 v[30:31], v[30:31], v[48:49] op_sel_hi:[1,0]
	v_pk_mul_f32 v[10:11], v[4:5], v[4:5]
	s_nop 0
	v_pk_fma_f32 v[10:11], v[8:9], v[8:9], v[10:11]
	s_nop 0
	v_pk_add_f32 v[6:7], v[10:11], v[6:7]
	s_nop 0
	v_pk_add_f32 v[12:13], v[10:11], v[6:7] op_sel:[1,0] op_sel_hi:[0,1]
	v_pk_mul_f32 v[6:7], v[36:37], v[48:49] op_sel_hi:[1,0]
	v_pk_mul_f32 v[10:11], v[20:21], v[48:49] op_sel_hi:[1,0]
	v_pk_mul_f32 v[14:15], v[6:7], v[6:7]
	s_nop 0
	v_pk_fma_f32 v[14:15], v[10:11], v[10:11], v[14:15]
	s_nop 0
	v_pk_add_f32 v[12:13], v[14:15], v[12:13]
	s_nop 0
	v_pk_add_f32 v[14:15], v[14:15], v[12:13] op_sel:[1,0] op_sel_hi:[0,1]
	v_pk_mul_f32 v[12:13], v[38:39], v[48:49] op_sel_hi:[1,0]
	s_nop 0
	v_pk_mul_f32 v[18:19], v[12:13], v[12:13]
	s_nop 0
	v_pk_fma_f32 v[18:19], v[16:17], v[16:17], v[18:19]
	s_nop 0
	v_pk_add_f32 v[14:15], v[18:19], v[14:15]
	s_nop 0
	v_pk_add_f32 v[20:21], v[18:19], v[14:15] op_sel:[1,0] op_sel_hi:[0,1]
	v_pk_mul_f32 v[14:15], v[40:41], v[48:49] op_sel_hi:[1,0]
	v_pk_mul_f32 v[18:19], v[24:25], v[48:49] op_sel_hi:[1,0]
	v_pk_mul_f32 v[22:23], v[14:15], v[14:15]
	v_pk_mul_f32 v[24:25], v[26:27], v[48:49] op_sel_hi:[1,0]
	v_pk_fma_f32 v[22:23], v[18:19], v[18:19], v[22:23]
	s_nop 0
	v_pk_add_f32 v[20:21], v[22:23], v[20:21]
	s_nop 0
	v_pk_add_f32 v[22:23], v[22:23], v[20:21] op_sel:[1,0] op_sel_hi:[0,1]
	v_pk_mul_f32 v[20:21], v[42:43], v[48:49] op_sel_hi:[1,0]
	s_nop 0
	v_pk_mul_f32 v[26:27], v[20:21], v[20:21]
	s_nop 0
	v_pk_fma_f32 v[26:27], v[24:25], v[24:25], v[26:27]
	s_nop 0
	v_pk_add_f32 v[22:23], v[26:27], v[22:23]
	s_nop 0
	v_pk_add_f32 v[32:33], v[26:27], v[22:23] op_sel:[1,0] op_sel_hi:[0,1]
	v_pk_mul_f32 v[22:23], v[44:45], v[48:49] op_sel_hi:[1,0]
	v_pk_mul_f32 v[26:27], v[28:29], v[48:49] op_sel_hi:[1,0]
	v_pk_mul_f32 v[28:29], v[22:23], v[22:23]
	s_nop 0
	v_pk_fma_f32 v[28:29], v[26:27], v[26:27], v[28:29]
	s_nop 0
	v_pk_add_f32 v[32:33], v[28:29], v[32:33]
	s_nop 0
	v_pk_add_f32 v[32:33], v[28:29], v[32:33] op_sel:[1,0] op_sel_hi:[0,1]
	v_pk_mul_f32 v[28:29], v[46:47], v[48:49] op_sel_hi:[1,0]
	s_nop 0
	v_pk_mul_f32 v[34:35], v[28:29], v[28:29]
	s_nop 0
	v_pk_fma_f32 v[34:35], v[30:31], v[30:31], v[34:35]
	s_nop 0
	v_pk_add_f32 v[32:33], v[34:35], v[32:33]
	s_nop 0
	v_pk_add_f32 v[32:33], v[34:35], v[32:33] op_sel:[1,0] op_sel_hi:[0,1]
	v_mov_b32_e32 v33, v32
	s_nop 1
	v_permlane32_swap_b32_e32 v32, v33
	s_and_saveexec_b64 s[0:1], s[38:39]
	s_cbranch_execz .LBB0_463
	s_lshl_b64 s[4:5], s[40:41], 16
	s_add_u32 s4, s14, s4
	s_addc_u32 s5, s15, s5
	v_add_f32_e32 v34, v32, v33
	v_lshl_add_u64 v[32:33], v[124:125], 2, s[4:5]
	global_atomic_add_f32 v[32:33], v34, off
	s_branch .LBB0_463
